# odd workgroups run the gMLP mixer before attention so its memory traffic overlaps other workgroups attention compute
# baseline (speedup 1.0000x reference)
; #define RP(k) for (int rep = 0; rep < 1 + ((REPMASK >> (k)) & 1); ++rep)
; #define RS do { if (rep) cg::this_grid().sync(); } while (0)
; #define SEAM(k) do { if (IN(k) && IN((k) + 1)) xcd_barrier(xbar); } while (0)
; __device__ __forceinline__ void attn_phase(const Params& p, LAS unsigned char* lds, int G) {
;     ...
;     float negsb;
;     {
;         float gq = fmaxf(fabsf(p.in[15][lane]), fabsf(p.in[15][64 + l32])), gk = fmaxf(fabsf(p.in[16][lane]), fabsf(p.in[16][64 + l32]));
; #pragma unroll
;         for (int o = 1; o < 64; o <<= 1) { gq = fmaxf(gq, __shfl_xor(gq, o)); gk = fmaxf(gk, __shfl_xor(gk, o)); }
;         negsb = -(96.f * gq * gk * QSCALE);
;     }
;     f32x16 negv;
; #pragma unroll
;     for (int e = 0; e < 16; ++e) negv[e] = negsb;
;     asm volatile("" : "+v"(negv));
; __global__ void __launch_bounds__(512, 2) mk_fwd(Params p) {
;     ...
;     if (IN(6)) RP(6) { RS; attn_phase(p, lds, G); gmlp_phase(p, lds, G); } SEAM(6);
.LBB0_628:
	s_cmp_lt_i32 s94, 7
	s_cselect_b64 s[4:5], -1, 0
	s_and_b64 s[28:29], s[4:5], s[0:1]
	s_andn2_b64 vcc, exec, s[28:29]
	s_cbranch_vccnz .LBB0_660
	s_mov_b32 s0, 0
	v_writelane_b32 v255, s0, 47
.Lattn_entry:
	s_waitcnt vmcnt(0)
	v_mov_b32_e32 v16, v166
	v_mbcnt_lo_u32_b32 v4, -1, 0
	v_and_b32_e32 v17, 63, v16
	v_and_b32_e32 v170, 31, v16
	v_lshlrev_b32_e32 v0, 2, v17
	v_lshlrev_b32_e32 v171, 2, v170
	s_waitcnt lgkmcnt(0)
	global_load_dword v1, v171, s[70:71] offset:256
	global_load_dword v2, v0, s[70:71]
	global_load_dword v3, v171, s[72:73] offset:256
	s_nop 0
	global_load_dword v0, v0, s[72:73]
	v_mbcnt_hi_u32_b32 v4, -1, v4
	v_and_b32_e32 v5, 64, v4
	v_xor_b32_e32 v6, 1, v4
	v_add_u32_e32 v5, 64, v5
	v_cmp_lt_i32_e32 vcc, v6, v5
	v_xor_b32_e32 v7, 2, v4
	v_xor_b32_e32 v8, 4, v4
	v_cndmask_b32_e32 v6, v4, v6, vcc
	v_lshlrev_b32_e32 v167, 2, v6
	v_cmp_lt_i32_e32 vcc, v7, v5
	v_xor_b32_e32 v9, 8, v4
	v_xor_b32_e32 v10, 16, v4
	v_cndmask_b32_e32 v6, v4, v7, vcc
	v_lshlrev_b32_e32 v168, 2, v6
	v_cmp_lt_i32_e32 vcc, v8, v5
	v_xor_b32_e32 v11, 32, v4
	s_cmpk_gt_i32 s2, 0x7ff
	v_cndmask_b32_e32 v6, v4, v8, vcc
	v_lshlrev_b32_e32 v6, 2, v6
	v_cmp_lt_i32_e32 vcc, v9, v5
	s_mov_b32 s31, 0
	v_readfirstlane_b32 s0, v16
	s_waitcnt vmcnt(3)
	v_max_f32_e64 v1, |v1|, |v1|
	s_waitcnt vmcnt(2)
	v_max_f32_e64 v2, |v2|, |v2|
	s_waitcnt vmcnt(1)
	v_max_f32_e64 v3, |v3|, |v3|
	s_waitcnt vmcnt(0)
	v_max_f32_e64 v0, |v0|, |v0|
	v_max_f32_e32 v1, v2, v1
	v_max_f32_e32 v0, v0, v3
	ds_bpermute_b32 v2, v167, v1
	ds_bpermute_b32 v3, v167, v0
	s_waitcnt lgkmcnt(1)
	v_max_f32_e32 v2, v2, v2
	s_waitcnt lgkmcnt(0)
	v_max_f32_e32 v3, v3, v3
	v_max_f32_e32 v1, v1, v2
	v_max_f32_e32 v0, v0, v3
	ds_bpermute_b32 v2, v168, v1
	ds_bpermute_b32 v3, v168, v0
	s_waitcnt lgkmcnt(1)
	v_max_f32_e32 v2, v2, v2
	s_waitcnt lgkmcnt(0)
	v_max_f32_e32 v3, v3, v3
	v_max_f32_e32 v1, v1, v2
	v_max_f32_e32 v0, v0, v3
	ds_bpermute_b32 v2, v6, v1
	ds_bpermute_b32 v3, v6, v0
	v_cndmask_b32_e32 v6, v4, v9, vcc
	v_lshlrev_b32_e32 v6, 2, v6
	v_cmp_lt_i32_e32 vcc, v10, v5
	s_waitcnt lgkmcnt(1)
	v_max_f32_e32 v2, v2, v2
	s_waitcnt lgkmcnt(0)
	v_max_f32_e32 v3, v3, v3
	v_max_f32_e32 v1, v1, v2
	v_max_f32_e32 v0, v0, v3
	ds_bpermute_b32 v2, v6, v1
	ds_bpermute_b32 v3, v6, v0
	v_cndmask_b32_e32 v6, v4, v10, vcc
	v_lshlrev_b32_e32 v6, 2, v6
	v_cmp_lt_i32_e32 vcc, v11, v5
	s_waitcnt lgkmcnt(1)
	v_max_f32_e32 v2, v2, v2
	s_waitcnt lgkmcnt(0)
	v_max_f32_e32 v3, v3, v3
	v_max_f32_e32 v1, v1, v2
	v_max_f32_e32 v0, v0, v3
	ds_bpermute_b32 v2, v6, v1
	ds_bpermute_b32 v3, v6, v0
	v_cndmask_b32_e32 v4, v4, v11, vcc
	v_lshlrev_b32_e32 v169, 2, v4
	s_waitcnt lgkmcnt(1)
	v_max_f32_e32 v2, v2, v2
	s_waitcnt lgkmcnt(0)
	v_max_f32_e32 v3, v3, v3
	v_max_f32_e32 v1, v1, v2
	v_max_f32_e32 v0, v0, v3
	ds_bpermute_b32 v2, v169, v1
	ds_bpermute_b32 v3, v169, v0
	s_waitcnt lgkmcnt(1)
	v_max_f32_e32 v2, v2, v2
	s_waitcnt lgkmcnt(0)
	v_max_f32_e32 v3, v3, v3
	v_max_f32_e32 v1, v1, v2
	v_max_f32_e32 v0, v0, v3
	v_mul_f32_e32 v1, 0x42c00000, v1
	v_mul_f32_e32 v0, v0, v1
	v_mul_f32_e32 v0, 0xbe16c740, v0
	v_mov_b32_e32 v1, v0
	v_mov_b32_e32 v2, v0
	v_mov_b32_e32 v3, v0
	v_mov_b32_e32 v4, v0
	v_mov_b32_e32 v5, v0
	v_mov_b32_e32 v6, v0
	v_mov_b32_e32 v7, v0
	v_mov_b32_e32 v8, v0
	v_mov_b32_e32 v9, v0
	v_mov_b32_e32 v10, v0
	v_mov_b32_e32 v11, v0
	v_mov_b32_e32 v12, v0
	v_mov_b32_e32 v13, v0
	v_mov_b32_e32 v14, v0
	v_mov_b32_e32 v15, v0
	s_cbranch_scc1 .LBB0_649
; #define RP(k) for (int rep = 0; rep < 1 + ((REPMASK >> (k)) & 1); ++rep)
; #define RS do { if (rep) cg::this_grid().sync(); } while (0)
; #define SEAM(k) do { if (IN(k) && IN((k) + 1)) xcd_barrier(xbar); } while (0)
; __device__ __forceinline__ void attn_phase(const Params& p, LAS unsigned char* lds, int G) {
;     ...
;     const int kr0 = tid / 12, kc0 = tid - kr0 * 12;
;     const int kr1 = (tid + 512) / 12, kc1 = (tid + 512) - kr1 * 12;
;     const int kr2 = (tid + 1024) / 12, kc2 = (tid + 1024) - kr2 * 12;
;     const int vr0 = tid >> 4, vc0 = tid & 15;
;     float negsb;
;     {
;         float gq = fmaxf(fabsf(p.in[15][lane]), fabsf(p.in[15][64 + l32])), gk = fmaxf(fabsf(p.in[16][lane]), fabsf(p.in[16][64 + l32]));
; #pragma unroll
;         for (int o = 1; o < 64; o <<= 1) { gq = fmaxf(gq, __shfl_xor(gq, o)); gk = fmaxf(gk, __shfl_xor(gk, o)); }
;         negsb = -(96.f * gq * gk * QSCALE);
;     }
;     f32x16 negv;
; #pragma unroll
;     for (int e = 0; e < 16; ++e) negv[e] = negsb;
;     asm volatile("" : "+v"(negv));
;     for (int it = blockIdx.x; it < 2048; it += G) {
;         const int kk = it >> 8, cc = it & 255, bh = cc >> 1, set = cc & 1;
;         const int qt = set ? (14 - 2 * kk + (kk & 1)) : (15 - 2 * kk - (kk & 1));
;         const int q0 = qt * 256 + 32 * wave, lim = q0 >> 6, nkt = 4 * qt + 4;
; __global__ void __launch_bounds__(512, 2) mk_fwd(Params p) {
;     ...
;     if (IN(6)) RP(6) { RS; attn_phase(p, lds, G); gmlp_phase(p, lds, G); } SEAM(6);
	v_add_u32_e32 v18, 0x200, v16
	s_mov_b32 s1, 0x2aaaaaab
	v_mul_hi_i32 v19, v18, s1
	v_lshrrev_b32_e32 v20, 31, v19
	v_ashrrev_i32_e32 v19, 1, v19
	v_add_u32_e32 v30, v19, v20
	v_mad_u64_u32 v[18:19], s[10:11], v30, -12, v[18:19]
	v_add_u32_e32 v20, 0x400, v16
	v_mul_hi_i32 v19, v20, s1
	v_lshrrev_b32_e32 v21, 31, v19
	v_ashrrev_i32_e32 v19, 1, v19
	s_add_u32 s4, s92, 0x36000000
	v_add_u32_e32 v19, v19, v21
	s_addc_u32 s5, s93, 0
	v_mad_u64_u32 v[20:21], s[10:11], v19, -12, v[20:21]
	s_add_u32 s6, s92, 0x3c000000
	v_mul_hi_i32 v21, v16, s1
	s_addc_u32 s7, s93, 0
	v_lshrrev_b32_e32 v22, 31, v21
	v_ashrrev_i32_e32 v21, 1, v21
	s_add_u32 s34, s92, 0x22000000
	v_add_u32_e32 v31, v21, v22
	s_addc_u32 s35, s93, 0
	v_mad_u64_u32 v[22:23], s[10:11], v31, -12, v[16:17]
	s_add_u32 s8, s92, 0x3380000
	v_ashrrev_i32_e32 v24, 4, v16
	s_movk_i32 s11, 0x60
	s_addc_u32 s9, s93, 0
	s_ashr_i32 s10, s0, 1
	v_mad_i64_i32 v[126:127], s[0:1], v31, s11, 0
	v_mad_i64_i32 v[130:131], s[0:1], v30, s11, 0
	v_mad_i64_i32 v[134:135], s[0:1], v19, s11, 0
	v_ashrrev_i32_e32 v25, 31, v24
	v_mov_b32_e32 v125, 0
	v_lshlrev_b64 v[138:139], 12, v[24:25]
	s_mov_b64 s[0:1], 0x20000
	v_and_b32_e32 v124, 32, v17
	v_lshl_add_u64 v[140:141], v[138:139], 0, s[0:1]
	v_lshl_add_u64 v[28:29], s[92:93], 0, v[124:125]
	s_mov_b64 s[0:1], 0x2a00000
	v_lshl_add_u64 v[142:143], v[28:29], 0, s[0:1]
	s_mov_b64 s[0:1], 0x2e00000
	v_lshl_add_u64 v[144:145], v[28:29], 0, s[0:1]
	s_movk_i32 s0, 0x108
	v_lshrrev_b32_e32 v21, 5, v17
	v_lshlrev_b32_e32 v128, 3, v22
	v_mul_lo_u32 v23, v24, s0
	s_movk_i32 s0, 0xd0
	v_ashrrev_i32_e32 v129, 31, v128
	v_lshlrev_b32_e32 v132, 3, v18
	v_lshlrev_b32_e32 v136, 3, v20
	v_lshlrev_b32_e32 v26, 3, v21
	v_lshlrev_b32_e32 v176, 4, v18
	v_lshlrev_b32_e32 v178, 4, v20
	v_mad_u32_u24 v18, v170, s0, 0
	v_mul_u32_u24_e32 v20, 56, v170
	v_lshl_add_u32 v179, v21, 4, v18
	v_add3_u32 v180, v18, v20, v26
	v_lshlrev_b32_e32 v18, 2, v21
	v_lshlrev_b64 v[20:21], 1, v[128:129]
	s_movk_i32 s11, 0xc0
	v_mul_lo_u32 v173, v31, s0
	v_mul_lo_u32 v175, v30, s0
	v_mul_lo_u32 v177, v19, s0
	v_mad_i64_i32 v[20:21], s[0:1], v31, s11, v[20:21]
	v_ashrrev_i32_e32 v133, 31, v132
	v_lshl_add_u64 v[20:21], s[92:93], 0, v[20:21]
	s_mov_b64 s[0:1], 0x36006000
	v_lshl_add_u64 v[148:149], v[20:21], 0, s[0:1]
	v_lshlrev_b64 v[20:21], 1, v[132:133]
	v_mad_i64_i32 v[20:21], s[14:15], v30, s11, v[20:21]
	v_ashrrev_i32_e32 v137, 31, v136
	v_lshl_add_u64 v[20:21], s[92:93], 0, v[20:21]
	v_and_b32_e32 v27, 15, v16
	v_lshl_add_u64 v[150:151], v[20:21], 0, s[0:1]
	v_lshlrev_b64 v[20:21], 1, v[136:137]
	v_lshlrev_b32_e32 v24, 4, v27
	v_mad_i64_i32 v[20:21], s[14:15], v19, s11, v[20:21]
	v_lshlrev_b32_e32 v16, 3, v27
	v_add3_u32 v172, 0, v23, v24
	v_add_u32_e32 v23, 0, v173
	v_lshlrev_b32_e32 v174, 4, v22
	v_add_u32_e32 v22, 0, v175
	v_add_u32_e32 v24, 0, v177
	v_lshl_add_u64 v[20:21], s[92:93], 0, v[20:21]
	s_andn2_b32 s10, s10, 31
	v_add_u32_e32 v181, 0x3400, v179
	v_cmp_gt_u32_e64 s[38:39], 32, v17
	v_lshl_add_u64 v[146:147], s[70:71], 0, v[124:125]
	v_lshl_add_u64 v[152:153], v[20:21], 0, s[0:1]
	v_lshlrev_b32_e32 v124, 1, v16
	v_lshlrev_b32_e32 v154, 1, v26
	v_mov_b32_e32 v182, 0x358637bd
	v_mov_b32_e32 v183, 0x260
	s_mov_b32 s11, 0x3e16c740
	v_add_u32_e32 v184, v23, v174
	v_add_u32_e32 v185, v22, v176
	v_add_u32_e32 v186, v24, v178
	s_mov_b64 s[36:37], 0x6000
	v_lshlrev_b32_e32 v156, 1, v18
	v_mov_b32_e32 v187, 0xc0000
	v_mov_b32_e32 v188, 0x600
	s_mov_b32 s44, s2
	s_lshr_b32 s14, s10, 5
	s_lshl_b32 s15, s14, 1
	s_sub_u32 s16, 15, s15
	s_cmp_lt_u32 s14, 4
	s_cselect_b32 s14, s15, s16
	s_lshl_b32 s10, s14, 5
	v_and_b32_e32 v249, 31, v166
	v_mul_u32_u24_e32 v249, 0x110, v249
	v_bfe_u32 v251, v166, 5, 1
	v_lshl_add_u32 v249, v251, 4, v249
	v_bfe_u32 v250, v166, 4, 5
	v_mul_u32_u24_e32 v250, 0x110, v250
	v_bfe_u32 v251, v166, 1, 3
	v_lshl_add_u32 v250, v251, 5, v250
	v_and_b32_e32 v251, 1, v166
	v_lshl_add_u32 v250, v251, 3, v250
	v_cmp_gt_u32_e32 vcc, 96, v166
	s_nop 3
	s_and_saveexec_b64 s[0:1], vcc
	v_lshlrev_b32_e32 v251, 2, v166
	global_load_dword v252, v251, s[70:71]
	v_add_u32_e32 v251, 0x1f000, v251
	s_waitcnt vmcnt(0)
	ds_write_b32 v251, v252
	s_mov_b64 exec, s[0:1]
	s_waitcnt lgkmcnt(0)
	s_barrier
	v_readlane_b32 s0, v255, 47
	s_nop 3
	s_and_b32 s1, s2, 1
	s_cmp_eq_u32 s0, 0
	s_cselect_b32 s1, s1, 0
	s_cmp_eq_u32 s1, 0
	s_cbranch_scc1 .Lattn_go
	s_mov_b32 s0, 1
	v_writelane_b32 v255, s0, 47
	s_branch .LBB0_649
.Lattn_go:
	s_branch .LBB0_632

; __device__ __forceinline__ void gmlp_phase(const Params& p, LAS unsigned char* lds, int G) {
;     ...
;     const int j = tid >> 2, part = tid & 3;
;     const int nunits = M / 128;
;     if ((int)blockIdx.x >= nunits) return;
;     u32x4 v0, v1, v2, v3;
;     { const u32x4* src = (const u32x4*)(GV + (size_t)(blockIdx.x * 128 + j) * 512 + part * 32); v0 = src[0]; v1 = src[1]; v2 = src[2]; v3 = src[3]; }
;     for (int unit = blockIdx.x; unit < nunits; unit += G) {
;         const int row0 = unit * 128;
;         for (int g = 0; g < 4; ++g) {
;             const int i = 32 * wi + l32; const size_t tok = (size_t)(row0 + i);
;             const int cb = g * 128 + 64 * wc + 4 * hi;
;             const bf16_t* ap = WSM + (size_t)(g * 128 + i) * 128 + 8 * hi;
;             bf16x8 wf[8]; u32x2 guv[8];
; #pragma unroll
;             for (int ks = 0; ks < 8; ++ks) wf[ks] = *(const bf16x8*)(ap + 16 * ks);
; #pragma unroll
;             for (int q = 0; q < 4; ++q) { guv[2 * q] = *(const u32x2*)(GU + tok * 512 + cb + 8 * q); guv[2 * q + 1] = *(const u32x2*)(GU + tok * 512 + cb + 32 + 8 * q); }
;             const float bi = bs[g * 128 + i];
.LBB0_649:
	v_readlane_b32 s0, v255, 47
	s_nop 3
	s_cmp_eq_u32 s0, 2
	s_cbranch_scc1 .LBB0_660
	s_cmpk_gt_i32 s2, 0x1ff
	v_mov_b32_e32 v0, v166
	s_cbranch_scc1 .Lgmlp_done
	s_add_u32 s30, s92, 0x3340000
	s_addc_u32 s31, s93, 0
	s_add_u32 s0, s92, 0x10000000
	v_ashrrev_i32_e32 v81, 2, v0
	s_addc_u32 s1, s93, 0
	s_lshl_b32 s6, s2, 7
	v_add_u32_e32 v76, s6, v81
	v_mov_b32_e32 v77, 0
	v_lshlrev_b32_e32 v1, 5, v0
	v_lshlrev_b64 v[2:3], 10, v[76:77]
	v_and_b32_e32 v1, 0x60, v1
	v_lshl_add_u64 v[2:3], s[0:1], 0, v[2:3]
	v_lshlrev_b32_e32 v4, 1, v1
	v_mov_b32_e32 v5, v77
	v_lshl_add_u64 v[2:3], v[2:3], 0, v[4:5]
	global_load_dwordx4 v[32:35], v[2:3], off offset:48
	global_load_dwordx4 v[36:39], v[2:3], off offset:32
	global_load_dwordx4 v[40:43], v[2:3], off offset:16
	global_load_dwordx4 v[44:47], v[2:3], off
	v_and_b32_e32 v2, 64, v0
	v_bfe_u32 v8, v0, 5, 1
	s_movk_i32 s4, 0xffe0
	v_lshl_or_b32 v80, v8, 2, v2
	v_lshlrev_b32_e32 v2, 4, v8
	v_mov_b32_e32 v3, v77
	v_bfi_b32 v78, s4, v81, v0
	v_lshl_add_u64 v[6:7], s[92:93], 0, v[2:3]
	s_mov_b64 s[4:5], 0x2900000
	v_lshl_add_u64 v[82:83], v[6:7], 0, s[4:5]
	v_add_u32_e32 v6, 0, v2
	v_and_b32_e32 v2, 0x5f, v0
	v_mul_u32_u24_e32 v7, 0x110, v2
	v_mul_u32_u24_e32 v1, 0x110, v1
	v_lshlrev_b32_e32 v2, 1, v81
	v_ashrrev_i32_e32 v79, 31, v78
	v_and_b32_e32 v9, 31, v0
	v_add3_u32 v132, 0, v1, v2
	v_lshlrev_b64 v[2:3], 8, v[78:79]
	v_and_b32_e32 v0, 3, v0
	s_waitcnt vmcnt(15)
	v_lshl_add_u64 v[84:85], s[0:1], 0, v[4:5]
	v_lshl_add_u64 v[2:3], v[82:83], 0, v[2:3]
	s_mov_b64 s[0:1], 0x18000
	v_lshlrev_b32_e32 v0, 6, v0
	v_mov_b32_e32 v1, v77
	v_and_b32_e32 v10, 0xffffffe0, v81
	v_lshl_add_u64 v[86:87], v[2:3], 0, s[0:1]
	v_lshlrev_b32_e32 v2, 2, v80
	v_mov_b32_e32 v3, v77
	s_waitcnt vmcnt(13)
	v_lshl_add_u64 v[92:93], s[92:93], 0, v[0:1]
	v_lshlrev_b32_e32 v0, 1, v80
	v_lshl_add_u64 v[90:91], s[56:57], 0, v[2:3]
	v_lshl_add_u64 v[94:95], s[92:93], 0, v[0:1]
	v_add_u32_e32 v0, s6, v10
	s_mov_b64 s[0:1], 0xe0
	v_cmp_eq_u32_e64 s[38:39], 0, v8
	v_lshl_add_u64 v[88:89], v[78:79], 2, s[60:61]
	s_lshl_b32 s4, s3, 7
	s_waitcnt vmcnt(12)
	v_or_b32_e32 v96, v0, v9
	v_lshl_add_u64 v[98:99], v[90:91], 0, s[0:1]
	v_mov_b32_e32 v79, 0x358637bd
	s_mov_b32 s5, 0xf800000
	v_mov_b32_e32 v133, 0x260
	v_add_u32_e32 v134, v6, v7
	v_mov_b32_e32 v100, v76
	s_mov_b32 s6, s2
	s_branch .LBB0_652

; #define RP(k) for (int rep = 0; rep < 1 + ((REPMASK >> (k)) & 1); ++rep)
; #define RS do { if (rep) cg::this_grid().sync(); } while (0)
; #define SEAM(k) do { if (IN(k) && IN((k) + 1)) xcd_barrier(xbar); } while (0)
; __global__ void __launch_bounds__(512, 2) mk_fwd(Params p) {
;     ...
;     if (IN(6)) RP(6) { RS; attn_phase(p, lds, G); gmlp_phase(p, lds, G); } SEAM(6);
.Lgmlp_done:
	v_readlane_b32 s0, v255, 47
	s_nop 3
	s_cmp_eq_u32 s0, 1
	s_cbranch_scc0 .LBB0_660
	s_mov_b32 s0, 2
	v_writelane_b32 v255, s0, 47
	s_branch .Lattn_entry
